# attention loop 1: K/V prefetch addresses via SGPR base + 32-bit lane offset; 64-bit VALU address math removed
# baseline (speedup 1.0000x reference)
; #define AT_LOADK(t_) do { const size_t kb_ = (size_t)(t_) * 64; rk0 = *(const u32x4*)(Kh + (kb_ + kkey0) * 96 + kpart0 * 8); if (tid < 256) rk1 = *(const u32x4*)(Kh + (kb_ + kkey1) * 96 + kpart1 * 8); } while (0)
; #define AT_LOADV(t_) do { rv = *(const u32x4*)(Vh + (size_t)vdv * S + (size_t)(t_) * 64 + vpart * 8); } while (0)
; #define AT_WRITEK(t_) do { LAS unsigned char* Ks_ = lds + ((t_) & 1) * AT_KT; *(LAS u32x4*)(Ks_ + kkey0 * AT_KROW + kpart0 * 16) = rk0; if (tid < 256) *(LAS u32x4*)(Ks_ + kkey1 * AT_KROW + kpart1 * 16) = rk1; } while (0)
; #define AT_STEPM(C0, C1, MC, N0, N1, MN, t_) do { \
;         AT_WRITEK((t_) + 1); AT_WRITEV(t_); \
;         __syncthreads(); \
;         AT_LOADK((t_) + 2); AT_LOADV((t_) + 1); \
;         AT_SM1(C0, C1, MC, t_, 0); MN = mref; AT_QK(N0, N1, (t_) + 1); AT_SM2(C0, C1, t_); \
;     } while (0)
; DI void attn_unit(int wv, int h, int qb, const bf16_t* QB, const bf16_t* KB, const bf16_t* VT, bf16_t* MIX, LAS unsigned char* lds) {
;     ...
;     f32x16 pA0, pA1, pB0 = {}, pB1 = {}; float mA = 0.f, mB = 0.f;
;     AT_LOADK(0); AT_WRITEK(0);
;     __syncthreads();
;     AT_LOADK(1); AT_LOADV(0);
;     AT_QK(pA0, pA1, 0);
;     int t = 0;
;     for (; t < 4 * qb; t += 2) {
;         AT_STEPM(pA0, pA1, mA, pB0, pB1, mB, t);
.LBB0_799:
	s_or_b64 exec, exec, s[0:1]
	v_mad_u32_u24 v2, v22, s37, 0
	v_add_u32_e32 v201, v2, v0
	ds_read_b128 v[2:5], v201
	ds_read_b128 v[12:15], v201 offset:32
	s_lshl_b64 s[40:41], s[88:89], 21
	v_readlane_b32 s0, v240, 7
	v_ashrrev_i32_e32 v38, 3, v9
	s_waitcnt lgkmcnt(1)
	v_mfma_f32_32x32x16_bf16 v[50:65], v[2:5], v[114:117], 0
	ds_read_b128 v[2:5], v201 offset:6656
	ds_read_b128 v[26:29], v201 offset:6688
	s_add_u32 s80, s0, s40
	v_ashrrev_i32_e32 v39, 31, v38
	v_readlane_b32 s0, v240, 8
	s_addc_u32 s81, s0, s41
	v_lshlrev_b64 v[40:41], 15, v[38:39]
	v_lshlrev_b32_e32 v0, 4, v8
	s_waitcnt lgkmcnt(1)
	v_mfma_f32_32x32x16_bf16 v[66:81], v[2:5], v[114:117], 0
	v_lshl_add_u64 v[2:3], s[80:81], 0, v[40:41]
	v_and_b32_e32 v158, 0x70, v0
	v_mov_b32_e32 v159, v1
	v_lshl_add_u64 v[2:3], v[2:3], 0, v[158:159]
	global_load_dwordx4 v[146:149], v[2:3], off
	ds_read_b128 v[2:5], v201 offset:64
	ds_read_b128 v[6:9], v201 offset:96
	v_mad_i64_i32 v[42:43], s[0:1], v10, s34, 0
	v_mfma_f32_32x32x16_bf16 v[50:65], v[12:15], v[118:121], v[50:65]
	ds_read_b128 v[10:13], v201 offset:6752
	s_mov_b32 s12, 0
	s_mov_b32 s13, s12
	v_add_u32_e32 v159, 0, v24
	v_mov_b64_e32 v[24:25], s[70:71]
	v_lshlrev_b32_e32 v0, 3, v178
	s_mov_b32 s14, s12
	s_waitcnt lgkmcnt(2)
	v_mfma_f32_32x32x16_bf16 v[50:65], v[2:5], v[122:125], v[50:65]
	ds_read_b128 v[2:5], v201 offset:6720
	s_mov_b32 s15, s12
	s_mov_b32 s16, s12
	s_mov_b32 s17, s12
	s_mov_b32 s18, s12
	s_mov_b32 s19, s12
	s_mov_b32 s20, s12
	v_mfma_f32_32x32x16_bf16 v[66:81], v[26:29], v[118:121], v[66:81]
	ds_read_b128 v[26:29], v201 offset:128
	ds_read_b128 v[30:33], v201 offset:6784
	ds_read_b128 v[34:37], v201 offset:160
	ds_read_b128 v[82:85], v201 offset:6816
	s_mov_b32 s21, s12
	s_mov_b32 s22, s12
	s_mov_b32 s23, s12
	s_mov_b32 s24, s12
	s_waitcnt lgkmcnt(4)
	v_mfma_f32_32x32x16_bf16 v[66:81], v[2:5], v[122:125], v[66:81]
	s_mov_b32 s25, s12
	s_mov_b32 s26, s12
	s_mov_b32 s27, s12
	v_lshl_add_u64 v[160:161], s[40:41], 0, v[40:41]
	v_or_b32_e32 v160, v160, v158
	s_lshl_b32 s29, s10, 2
	s_mov_b32 s89, 3
	v_mfma_f32_32x32x16_bf16 v[50:65], v[6:9], v[126:129], v[50:65]
	v_or_b32_e32 v156, 0x100, v160
	v_mov_b32_e32 v157, v161
	v_mov_b32_e32 v205, 0
	s_mov_b32 s90, 5
	v_mov_b32_e32 v203, 0
	v_mfma_f32_32x32x16_bf16 v[66:81], v[10:13], v[126:129], v[66:81]
	v_mov_b64_e32 v[2:3], s[12:13]
	v_mov_b64_e32 v[16:17], s[26:27]
	v_mov_b64_e32 v[4:5], s[14:15]
	v_mov_b64_e32 v[6:7], s[16:17]
	v_mov_b64_e32 v[8:9], s[18:19]
	v_mov_b64_e32 v[10:11], s[20:21]
	v_mov_b64_e32 v[12:13], s[22:23]
	s_waitcnt lgkmcnt(3)
	v_mfma_f32_32x32x16_bf16 v[50:65], v[26:29], v[130:133], v[50:65]
	v_mul_u32_u24_e32 v27, 0x88, v22
	v_mad_i64_i32 v[22:23], s[0:1], v23, s34, v[24:25]
	v_add_u32_e32 v26, 0, v0
	v_lshl_add_u64 v[150:151], v[20:21], 1, v[22:23]
	v_lshl_add_u64 v[20:21], s[70:71], 0, v[42:43]
	v_mov_b64_e32 v[14:15], s[24:25]
	s_waitcnt lgkmcnt(2)
	v_mfma_f32_32x32x16_bf16 v[66:81], v[30:33], v[130:133], v[66:81]
	v_mul_lo_u32 v0, v38, s38
	v_lshl_add_u64 v[152:153], v[18:19], 1, v[20:21]
	v_add_u32_e32 v179, v26, v27
	v_mov_b64_e32 v[32:33], v[16:17]
	v_add_u32_e32 v0, 0, v0
	v_mov_b64_e32 v[30:31], v[14:15]
	v_mov_b64_e32 v[28:29], v[12:13]
	s_waitcnt lgkmcnt(1)
	v_mfma_f32_32x32x16_bf16 v[50:65], v[34:37], v[134:137], v[50:65]
	v_mov_b64_e32 v[48:49], v[16:17]
	v_mov_b64_e32 v[26:27], v[10:11]
	v_mov_b64_e32 v[24:25], v[8:9]
	v_mov_b64_e32 v[22:23], v[6:7]
	v_mov_b64_e32 v[20:21], v[4:5]
	v_mov_b64_e32 v[18:19], v[2:3]
	v_mov_b64_e32 v[46:47], v[14:15]
	s_waitcnt lgkmcnt(0)
	v_mfma_f32_32x32x16_bf16 v[66:81], v[82:85], v[134:137], v[66:81]
	v_mov_b64_e32 v[44:45], v[12:13]
	v_mov_b64_e32 v[42:43], v[10:11]
	v_mov_b64_e32 v[40:41], v[8:9]
	v_mov_b64_e32 v[38:39], v[6:7]
	v_mov_b64_e32 v[36:37], v[4:5]
	v_mov_b64_e32 v[34:35], v[2:3]
	s_add_u32 s52, s94, 0xad71000
	s_addc_u32 s53, s95, 0
	s_add_u32 s54, s94, 0xad74000
	s_addc_u32 s55, s95, 0
	s_add_u32 s56, s94, 0xc56b000
	s_addc_u32 s57, s95, 0
	s_waitcnt vmcnt(1)
	ds_write_b128 v190, v[142:145] offset:13312
	s_and_saveexec_b64 s[8:9], s[6:7]
	s_branch .LBB0_801
.LBB0_800:
	s_mov_b32 s89, s1
	v_add_u32_e32 v156, 0x100, v156
	s_mov_b32 s90, s0
	s_waitcnt vmcnt(1)
	ds_write_b128 v190, v[142:145] offset:13312
	s_and_saveexec_b64 s[8:9], s[6:7]
.LBB0_801:
	v_add_u32_e32 v82, v159, v191
	ds_write_b128 v82, v[138:141] offset:13312
	s_or_b64 exec, exec, s[8:9]
	v_add3_u32 v202, v0, v158, s33
	s_waitcnt vmcnt(0)
	ds_write2_b64 v202, v[146:147], v[148:149] offset1:1
	s_waitcnt lgkmcnt(0)
	s_barrier
	global_load_dwordx4 v[142:145], v152, s[52:53]
	s_and_saveexec_b64 s[8:9], s[6:7]
	s_cbranch_execz .LBB0_804
	global_load_dwordx4 v[138:141], v150, s[52:53]
.LBB0_804:
	s_or_b64 exec, exec, s[8:9]
	global_load_dwordx4 v[146:149], v160, s[56:57] offset:128
	v_max_f32_e32 v84, v50, v50
	v_max_f32_e32 v83, v51, v51
	v_max_f32_e32 v83, v84, v83
	v_max3_f32 v84, v52, v53, v67
	v_max3_f32 v83, v83, v66, v68
	v_max3_f32 v83, v83, v69, v54
	v_max3_f32 v84, v84, v56, v57
	v_max3_f32 v83, v83, v55, v70
	v_max3_f32 v84, v84, v72, v73
	v_max3_f32 v83, v83, v71, v58
	v_max3_f32 v84, v84, v60, v61
	v_max3_f32 v83, v83, v59, v74
	v_max3_f32 v84, v84, v76, v77
	v_max3_f32 v83, v83, v75, v62
	v_max3_f32 v84, v84, v64, v65
	v_max3_f32 v83, v83, v63, v78
	v_max3_f32 v84, v84, v80, v81
	v_max3_f32 v83, v83, v79, v84
	v_mov_b32_e32 v84, v83
	s_nop 1
	v_permlane32_swap_b32_e32 v83, v84
	v_max_f32_e32 v84, v84, v84
	v_max_f32_e32 v83, v83, v83
	v_sub_f32_e32 v82, v205, v205
	v_max_f32_e32 v83, v83, v84
	s_cmp_eq_u32 s12, 0
	s_cselect_b64 s[10:11], -1, 0
	s_cmp_lg_u32 s12, 0
	v_sub_f32_e32 v83, v83, v82
	s_cbranch_scc0 .LBB0_811
	v_cmp_lt_f32_e32 vcc, s97, v83
	v_cmp_neq_f32_e64 s[8:9], 0, v82
	s_or_b64 vcc, s[8:9], vcc
	s_mov_b64 s[14:15], 0
	s_mov_b64 s[8:9], 0
	s_cbranch_vccz .LBB0_807
	v_max_f32_e32 v84, v83, v83
	v_max_f32_e32 v84, 0, v84
	s_mov_b64 s[8:9], -1

.LBB0_813:
	ds_read_b128 v[98:101], v201 offset:13312
	ds_read_b128 v[102:105], v201 offset:13344
	v_add_u32_e32 v206, 0x6800, v179
	v_exp_f32_e32 v50, v50
	v_exp_f32_e32 v51, v51
	s_waitcnt lgkmcnt(1)
	v_mfma_f32_32x32x16_bf16 v[82:97], v[98:101], v[114:117], v[34:49]
	v_exp_f32_e32 v52, v52
	v_exp_f32_e32 v53, v53
	v_exp_f32_e32 v54, v54
	v_exp_f32_e32 v55, v55
	v_exp_f32_e32 v56, v56
	v_exp_f32_e32 v57, v57
	v_add_u32_e32 v207, 0x7800, v179
	s_waitcnt lgkmcnt(0)
	v_mfma_f32_32x32x16_bf16 v[82:97], v[102:105], v[118:121], v[82:97]
	ds_read_b128 v[98:101], v201 offset:13376
	ds_read_b128 v[102:105], v201 offset:13408
	v_exp_f32_e32 v58, v58
	v_exp_f32_e32 v59, v59
	v_exp_f32_e32 v60, v60
	v_exp_f32_e32 v61, v61
	v_exp_f32_e32 v62, v62
	v_exp_f32_e32 v63, v63
	s_waitcnt lgkmcnt(1)
	v_mfma_f32_32x32x16_bf16 v[82:97], v[98:101], v[122:125], v[82:97]
	v_exp_f32_e32 v64, v64
	v_exp_f32_e32 v65, v65
	v_exp_f32_e32 v66, v66
	v_exp_f32_e32 v67, v67
	v_exp_f32_e32 v68, v68
	v_exp_f32_e32 v69, v69
	v_exp_f32_e32 v70, v70
	s_waitcnt lgkmcnt(0)
	v_mfma_f32_32x32x16_bf16 v[82:97], v[102:105], v[126:129], v[82:97]
	ds_read_b128 v[98:101], v201 offset:13440
	ds_read_b128 v[102:105], v201 offset:13472
	ds_read_b128 v[170:173], v201 offset:19968
	ds_read_b128 v[174:177], v201 offset:20000
	v_exp_f32_e32 v71, v71
	v_exp_f32_e32 v72, v72
	v_exp_f32_e32 v73, v73
	v_exp_f32_e32 v74, v74
	v_exp_f32_e32 v75, v75
	s_waitcnt lgkmcnt(3)
	v_mfma_f32_32x32x16_bf16 v[82:97], v[98:101], v[130:133], v[82:97]
	v_exp_f32_e32 v76, v76
	v_exp_f32_e32 v77, v77
	v_exp_f32_e32 v78, v78
	v_exp_f32_e32 v79, v79
	v_exp_f32_e32 v80, v80
	v_exp_f32_e32 v81, v81
	s_waitcnt lgkmcnt(2)
	v_mfma_f32_32x32x16_bf16 v[82:97], v[102:105], v[134:137], v[82:97]
	s_waitcnt lgkmcnt(1)
	v_mfma_f32_32x32x16_bf16 v[98:113], v[170:173], v[114:117], v[34:49]
	s_waitcnt lgkmcnt(0)
	v_mfma_f32_32x32x16_bf16 v[98:113], v[174:177], v[118:121], v[98:113]
	ds_read_b128 v[170:173], v201 offset:20032
	ds_read_b128 v[174:177], v201 offset:20064
	s_waitcnt lgkmcnt(1)
	v_mfma_f32_32x32x16_bf16 v[98:113], v[170:173], v[122:125], v[98:113]
	s_waitcnt lgkmcnt(0)
	v_mfma_f32_32x32x16_bf16 v[98:113], v[174:177], v[126:129], v[98:113]
	ds_read_b128 v[170:173], v201 offset:20096
	ds_read_b128 v[174:177], v201 offset:20128
	ds_read2_b64 v[180:183], v206 offset0:4 offset1:6
	s_waitcnt lgkmcnt(2)
	v_mfma_f32_32x32x16_bf16 v[98:113], v[170:173], v[130:133], v[98:113]
	ds_read2_b64 v[170:173], v206 offset1:2
	s_waitcnt lgkmcnt(2)
	v_mfma_f32_32x32x16_bf16 v[98:113], v[174:177], v[134:137], v[98:113]
	v_cvt_pk_bf16_f32 v174, v50, v51
	v_cvt_pk_bf16_f32 v175, v52, v53
	v_cvt_pk_bf16_f32 v176, v54, v55
	v_cvt_pk_bf16_f32 v177, v56, v57
	s_waitcnt lgkmcnt(0)
	s_nop 0
	v_mfma_f32_32x32x16_bf16 v[2:17], v[170:173], v[174:177], v[2:17]
	ds_read2_b64 v[170:173], v207 offset0:32 offset1:34
	s_waitcnt lgkmcnt(0)
	v_mfma_f32_32x32x16_bf16 v[18:33], v[170:173], v[174:177], v[18:33]
	ds_read2_b64 v[174:177], v207 offset0:36 offset1:38
	v_cvt_pk_bf16_f32 v170, v58, v59
	v_cvt_pk_bf16_f32 v171, v60, v61
	v_cvt_pk_bf16_f32 v172, v62, v63
	v_cvt_pk_bf16_f32 v173, v64, v65
	s_nop 1
	v_mfma_f32_32x32x16_bf16 v[2:17], v[180:183], v[170:173], v[2:17]
	ds_read2_b64 v[180:183], v206 offset0:8 offset1:10
	s_waitcnt lgkmcnt(1)
	v_mfma_f32_32x32x16_bf16 v[18:33], v[174:177], v[170:173], v[18:33]
	ds_read2_b64 v[174:177], v207 offset0:40 offset1:42
	v_cvt_pk_bf16_f32 v170, v66, v67
	v_cvt_pk_bf16_f32 v171, v68, v69
	v_cvt_pk_bf16_f32 v172, v70, v71
	v_cvt_pk_bf16_f32 v173, v72, v73
	s_waitcnt lgkmcnt(1)
	s_nop 0
	v_mfma_f32_32x32x16_bf16 v[2:17], v[180:183], v[170:173], v[2:17]
	ds_read2_b64 v[180:183], v206 offset0:12 offset1:14
	s_waitcnt lgkmcnt(1)
	v_mfma_f32_32x32x16_bf16 v[18:33], v[174:177], v[170:173], v[18:33]
	ds_read2_b64 v[174:177], v207 offset0:44 offset1:46
	v_cvt_pk_bf16_f32 v170, v74, v75
	v_cvt_pk_bf16_f32 v171, v76, v77
	v_cvt_pk_bf16_f32 v172, v78, v79
	v_cvt_pk_bf16_f32 v173, v80, v81
	s_waitcnt vmcnt(1)
	ds_write_b128 v190, v[142:145]
	s_waitcnt lgkmcnt(2)
	v_mfma_f32_32x32x16_bf16 v[2:17], v[180:183], v[170:173], v[2:17]
	s_waitcnt lgkmcnt(1)
	v_mfma_f32_32x32x16_bf16 v[18:33], v[174:177], v[170:173], v[18:33]
	s_and_saveexec_b64 s[8:9], s[6:7]
	v_add_u32_e32 v142, v159, v191
	ds_write_b128 v142, v[138:141]
	s_or_b64 exec, exec, s[8:9]
	v_add3_u32 v208, v0, v158, s4
	s_waitcnt vmcnt(0)
	ds_write2_b64 v208, v[146:147], v[148:149] offset1:1
	s_waitcnt lgkmcnt(0)
	s_barrier
	global_load_dwordx4 v[142:145], v152, s[54:55]
	s_and_saveexec_b64 s[8:9], s[6:7]
	s_cbranch_execz .LBB0_817
	global_load_dwordx4 v[138:141], v150, s[54:55]
.LBB0_817:
	s_or_b64 exec, exec, s[8:9]
	global_load_dwordx4 v[146:149], v160, s[56:57] offset:256
	v_add_f32_e32 v50, v66, v50
	v_add_u32_e32 v150, 0x6000, v150
	v_add_u32_e32 v152, 0x6000, v152
	v_add_u32_e32 v160, 0x100, v160
	v_add_f32_e32 v51, v67, v51
	v_add_f32_e32 v50, 0, v50
	v_add_f32_e32 v52, v68, v52
	v_add_f32_e32 v50, v51, v50
	v_add_f32_e32 v53, v69, v53
	v_add_f32_e32 v50, v52, v50
	v_add_f32_e32 v54, v70, v54
	v_add_f32_e32 v50, v53, v50
	v_max_f32_e32 v51, v83, v83
	v_max_f32_e32 v52, v82, v82
	v_add_f32_e32 v55, v71, v55
	v_add_f32_e32 v50, v54, v50
	v_max_f32_e32 v51, v52, v51
	v_add_f32_e32 v56, v72, v56
	v_add_f32_e32 v50, v55, v50
	v_max3_f32 v52, v84, v85, v99
	v_max3_f32 v51, v51, v98, v100
	v_add_f32_e32 v57, v73, v57
	v_add_f32_e32 v50, v56, v50
	v_max3_f32 v51, v51, v101, v86
	v_max3_f32 v52, v52, v88, v89
	v_add_f32_e32 v58, v74, v58
	v_add_f32_e32 v50, v57, v50
	v_max3_f32 v51, v51, v87, v102
	v_max3_f32 v52, v52, v104, v105
	v_add_f32_e32 v59, v75, v59
	v_add_f32_e32 v50, v58, v50
	v_max3_f32 v51, v51, v103, v90
	v_max3_f32 v52, v52, v92, v93
	v_add_f32_e32 v60, v76, v60
	v_add_f32_e32 v50, v59, v50
	v_max3_f32 v51, v51, v91, v106
	v_max3_f32 v52, v52, v108, v109
	v_add_f32_e32 v61, v77, v61
	v_add_f32_e32 v50, v60, v50
	v_max3_f32 v51, v51, v107, v94
	v_max3_f32 v52, v52, v96, v97
	v_add_f32_e32 v62, v78, v62
	v_add_f32_e32 v50, v61, v50
	v_max3_f32 v51, v51, v95, v110
	v_max3_f32 v52, v52, v112, v113
	v_add_f32_e32 v63, v79, v63
	v_add_f32_e32 v50, v62, v50
	v_max3_f32 v51, v51, v111, v52
	v_add_f32_e32 v64, v80, v64
	v_add_f32_e32 v50, v63, v50
	v_mov_b32_e32 v52, v51
	v_add_f32_e32 v65, v81, v65
	v_add_f32_e32 v50, v64, v50
	v_permlane32_swap_b32_e32 v51, v52
	v_add_f32_e32 v50, v65, v50
	v_max_f32_e32 v52, v52, v52
	v_max_f32_e32 v51, v51, v51
	v_add_f32_e32 v180, v203, v50
	v_sub_f32_e32 v50, v204, v204
	v_max_f32_e32 v51, v51, v52
	v_sub_f32_e32 v51, v51, v50
	v_cmp_lt_f32_e32 vcc, s97, v51
	v_cmp_neq_f32_e64 s[8:9], 0, v50
	s_or_b64 vcc, s[8:9], vcc
	s_cbranch_vccz .LBB0_819
	v_max_f32_e32 v34, v51, v51
	v_max_f32_e32 v35, 0, v34
	v_exp_f32_e64 v36, -v35
	v_add_f32_e32 v34, v50, v35
	v_add_f32_e32 v205, v204, v35
	v_pk_add_f32 v[82:83], v[82:83], v[34:35] op_sel_hi:[1,0] neg_lo:[0,1] neg_hi:[0,1]
	v_pk_add_f32 v[98:99], v[98:99], v[34:35] op_sel_hi:[1,0] neg_lo:[0,1] neg_hi:[0,1]
	v_pk_add_f32 v[84:85], v[84:85], v[34:35] op_sel_hi:[1,0] neg_lo:[0,1] neg_hi:[0,1]
	v_pk_add_f32 v[100:101], v[100:101], v[34:35] op_sel_hi:[1,0] neg_lo:[0,1] neg_hi:[0,1]
	v_pk_add_f32 v[86:87], v[86:87], v[34:35] op_sel_hi:[1,0] neg_lo:[0,1] neg_hi:[0,1]
	v_pk_add_f32 v[102:103], v[102:103], v[34:35] op_sel_hi:[1,0] neg_lo:[0,1] neg_hi:[0,1]
	v_pk_add_f32 v[88:89], v[88:89], v[34:35] op_sel_hi:[1,0] neg_lo:[0,1] neg_hi:[0,1]
	v_pk_add_f32 v[104:105], v[104:105], v[34:35] op_sel_hi:[1,0] neg_lo:[0,1] neg_hi:[0,1]
	v_pk_add_f32 v[90:91], v[90:91], v[34:35] op_sel_hi:[1,0] neg_lo:[0,1] neg_hi:[0,1]
	v_pk_add_f32 v[106:107], v[106:107], v[34:35] op_sel_hi:[1,0] neg_lo:[0,1] neg_hi:[0,1]
	v_pk_add_f32 v[92:93], v[92:93], v[34:35] op_sel_hi:[1,0] neg_lo:[0,1] neg_hi:[0,1]
	v_pk_add_f32 v[108:109], v[108:109], v[34:35] op_sel_hi:[1,0] neg_lo:[0,1] neg_hi:[0,1]
	v_pk_add_f32 v[94:95], v[94:95], v[34:35] op_sel_hi:[1,0] neg_lo:[0,1] neg_hi:[0,1]
	v_pk_add_f32 v[110:111], v[110:111], v[34:35] op_sel_hi:[1,0] neg_lo:[0,1] neg_hi:[0,1]
	v_pk_add_f32 v[96:97], v[96:97], v[34:35] op_sel_hi:[1,0] neg_lo:[0,1] neg_hi:[0,1]
	v_pk_add_f32 v[112:113], v[112:113], v[34:35] op_sel_hi:[1,0] neg_lo:[0,1] neg_hi:[0,1]
	v_xor_b32_e32 v34, 0x80000000, v205
	v_pk_mul_f32 v[16:17], v[16:17], v[36:37] op_sel_hi:[1,0]
	v_pk_mul_f32 v[14:15], v[14:15], v[36:37] op_sel_hi:[1,0]
	v_pk_mul_f32 v[12:13], v[12:13], v[36:37] op_sel_hi:[1,0]
	v_pk_mul_f32 v[10:11], v[10:11], v[36:37] op_sel_hi:[1,0]
	v_pk_mul_f32 v[8:9], v[8:9], v[36:37] op_sel_hi:[1,0]
	v_pk_mul_f32 v[6:7], v[6:7], v[36:37] op_sel_hi:[1,0]
	v_pk_mul_f32 v[4:5], v[4:5], v[36:37] op_sel_hi:[1,0]
	v_pk_mul_f32 v[2:3], v[2:3], v[36:37] op_sel_hi:[1,0]
	v_pk_mul_f32 v[32:33], v[32:33], v[36:37] op_sel_hi:[1,0]
	v_pk_mul_f32 v[30:31], v[30:31], v[36:37] op_sel_hi:[1,0]
	v_pk_mul_f32 v[28:29], v[28:29], v[36:37] op_sel_hi:[1,0]
	v_pk_mul_f32 v[26:27], v[26:27], v[36:37] op_sel_hi:[1,0]
	v_pk_mul_f32 v[24:25], v[24:25], v[36:37] op_sel_hi:[1,0]
	v_pk_mul_f32 v[22:23], v[22:23], v[36:37] op_sel_hi:[1,0]
	v_pk_mul_f32 v[20:21], v[20:21], v[36:37] op_sel_hi:[1,0]
	v_pk_mul_f32 v[18:19], v[18:19], v[36:37] op_sel_hi:[1,0]
	v_mul_f32_e32 v180, v180, v36
	v_mov_b32_e32 v35, v34
	v_mov_b32_e32 v36, v34
	v_mov_b32_e32 v37, v34
	v_mov_b32_e32 v38, v34
	v_mov_b32_e32 v39, v34
	v_mov_b32_e32 v40, v34
	v_mov_b32_e32 v41, v34
	v_mov_b32_e32 v42, v34
	v_mov_b32_e32 v43, v34
	v_mov_b32_e32 v44, v34
	v_mov_b32_e32 v45, v34
	v_mov_b32_e32 v46, v34
	v_mov_b32_e32 v47, v34
	v_mov_b32_e32 v48, v34
	v_mov_b32_e32 v49, v34
	s_branch .LBB0_820

; #define AT_STEPM(C0, C1, MC, N0, N1, MN, t_) do { \
;         AT_WRITEK((t_) + 1); AT_WRITEV(t_); \
;         __syncthreads(); \
;         AT_LOADK((t_) + 2); AT_LOADV((t_) + 1); \
;         AT_SM1(C0, C1, MC, t_, 0); MN = mref; AT_QK(N0, N1, (t_) + 1); AT_SM2(C0, C1, t_); \
;     } while (0)
; DI void attn_unit(int wv, int h, int qb, const bf16_t* QB, const bf16_t* KB, const bf16_t* VT, bf16_t* MIX, LAS unsigned char* lds) {
;     ...
;         AT_STEPM(pA0, pA1, mA, pB0, pB1, mB, t);
;         AT_STEPM(pB0, pB1, mB, pA0, pA1, mA, t + 1);
.LBB0_820:
	ds_read_b128 v[66:69], v201
	ds_read_b128 v[70:73], v201 offset:32
	v_add_u32_e32 v209, 0x8800, v179
	v_exp_f32_e32 v163, v86
	v_exp_f32_e32 v162, v87
	s_waitcnt lgkmcnt(1)
	v_mfma_f32_32x32x16_bf16 v[50:65], v[66:69], v[114:117], v[34:49]
	v_exp_f32_e32 v82, v82
	v_exp_f32_e32 v83, v83
	v_exp_f32_e32 v84, v84
	v_exp_f32_e32 v85, v85
	v_exp_f32_e32 v87, v104
	v_exp_f32_e32 v86, v105
	s_waitcnt lgkmcnt(0)
	v_mfma_f32_32x32x16_bf16 v[50:65], v[70:73], v[118:121], v[50:65]
	ds_read_b128 v[66:69], v201 offset:64
	ds_read_b128 v[70:73], v201 offset:96
	v_exp_f32_e32 v175, v102
	v_exp_f32_e32 v174, v103
	v_cvt_pk_bf16_f32 v102, v82, v83
	v_cvt_pk_bf16_f32 v103, v84, v85
	v_cvt_pk_bf16_f32 v104, v163, v162
	v_exp_f32_e32 v177, v96
	s_waitcnt lgkmcnt(1)
	v_mfma_f32_32x32x16_bf16 v[50:65], v[66:69], v[122:125], v[50:65]
	ds_read_b128 v[66:69], v201 offset:128
	v_exp_f32_e32 v176, v97
	v_exp_f32_e32 v98, v98
	v_exp_f32_e32 v99, v99
	v_exp_f32_e32 v100, v100
	v_exp_f32_e32 v101, v101
	v_add_f32_e32 v181, v98, v82
	s_waitcnt lgkmcnt(1)
	v_mfma_f32_32x32x16_bf16 v[50:65], v[70:73], v[126:129], v[50:65]
	ds_read_b128 v[166:169], v201 offset:6656
	ds_read_b128 v[170:173], v201 offset:6688
	ds_read_b128 v[182:185], v201 offset:6720
	ds_read_b128 v[186:189], v201 offset:6752
	ds_read_b128 v[70:73], v201 offset:160
	ds_read_b128 v[210:213], v201 offset:6784
	ds_read_b128 v[214:217], v201 offset:6816
	v_add_f32_e32 v203, v99, v83
	v_add_f32_e32 v181, 0, v181
	v_add_f32_e32 v228, v100, v84
	v_add_f32_e32 v181, v203, v181
	v_add_f32_e32 v229, v101, v85
	s_waitcnt lgkmcnt(7)
	v_mfma_f32_32x32x16_bf16 v[50:65], v[66:69], v[130:133], v[50:65]
	v_add_f32_e64 v218, v174, v162
	v_add_f32_e64 v219, v175, v163
	s_add_i32 s12, s12, 2
	s_add_i32 s0, s90, 2
	s_add_i32 s1, s89, 2
	s_waitcnt lgkmcnt(2)
	v_mfma_f32_32x32x16_bf16 v[50:65], v[70:73], v[134:137], v[50:65]
	s_cmp_ge_u32 s12, s29
	v_mfma_f32_32x32x16_bf16 v[66:81], v[166:169], v[114:117], v[34:49]
	v_exp_f32_e32 v167, v88
	v_exp_f32_e32 v166, v89
	v_exp_f32_e32 v169, v90
	v_exp_f32_e32 v89, v106
	v_exp_f32_e32 v168, v91
	v_exp_f32_e32 v88, v107
	v_exp_f32_e32 v91, v108
	v_mfma_f32_32x32x16_bf16 v[66:81], v[170:173], v[118:121], v[66:81]
	v_exp_f32_e32 v90, v109
	ds_read2_b64 v[106:109], v209 offset0:64 offset1:66
	v_exp_f32_e32 v171, v92
	v_exp_f32_e32 v170, v93
	v_exp_f32_e32 v93, v110
	v_exp_f32_e32 v92, v111
	v_mfma_f32_32x32x16_bf16 v[66:81], v[182:185], v[122:125], v[66:81]
	v_cvt_pk_bf16_f32 v105, v167, v166
	v_exp_f32_e32 v173, v94
	v_exp_f32_e32 v172, v95
	v_exp_f32_e32 v95, v112
	v_exp_f32_e32 v94, v113
	ds_read2_b64 v[110:113], v209 offset0:68 offset1:70
	v_add_f32_e32 v220, v86, v166
	v_add_f32_e32 v221, v87, v167
	v_mfma_f32_32x32x16_bf16 v[66:81], v[186:189], v[126:129], v[66:81]
	v_add_f32_e32 v222, v88, v168
	v_add_f32_e32 v223, v89, v169
	v_add_f32_e32 v96, v90, v170
	v_add_f32_e32 v97, v91, v171
	v_add_f32_e32 v224, v92, v172
	v_add_f32_e32 v225, v93, v173
	v_add_f32_e32 v226, v94, v176
	v_add_f32_e32 v227, v95, v177
	s_waitcnt lgkmcnt(3)
	v_mfma_f32_32x32x16_bf16 v[66:81], v[210:213], v[130:133], v[66:81]
	v_add_u32_e32 v210, 0x9800, v179
	ds_read2_b64 v[182:185], v210 offset0:96 offset1:98
	s_nop 0
	v_cvt_pk_bf16_f32 v212, v89, v88
	s_waitcnt lgkmcnt(2)
	v_mfma_f32_32x32x16_bf16 v[2:17], v[106:109], v[102:105], v[2:17]
	v_cvt_pk_bf16_f32 v106, v169, v168
	v_cvt_pk_bf16_f32 v107, v171, v170
	v_cvt_pk_bf16_f32 v108, v173, v172
	v_cvt_pk_bf16_f32 v109, v177, v176
	s_waitcnt lgkmcnt(0)
	v_mfma_f32_32x32x16_bf16 v[18:33], v[182:185], v[102:105], v[18:33]
	ds_read2_b64 v[102:105], v210 offset0:100 offset1:102
	v_cvt_pk_bf16_f32 v184, v175, v174
	v_cvt_pk_bf16_f32 v185, v87, v86
	v_cvt_pk_bf16_f32 v182, v98, v99
	v_cvt_pk_bf16_f32 v183, v100, v101
	v_mfma_f32_32x32x16_bf16 v[2:17], v[110:113], v[106:109], v[2:17]
	ds_read2_b64 v[110:113], v209 offset0:72 offset1:74
	ds_read2_b64 v[186:189], v210 offset0:104 offset1:106
	s_waitcnt lgkmcnt(2)
	v_mfma_f32_32x32x16_bf16 v[18:33], v[102:105], v[106:109], v[18:33]
	s_waitcnt lgkmcnt(1)
	v_mfma_f32_32x32x16_bf16 v[2:17], v[110:113], v[182:185], v[2:17]
	v_add_f32_e32 v110, v228, v181
	v_add_f32_e32 v110, v229, v110
	v_add_f32_e32 v110, v219, v110
	v_add_f32_e32 v110, v218, v110
	v_add_f32_e32 v110, v221, v110
	v_add_f32_e32 v110, v220, v110
	v_add_f32_e32 v110, v223, v110
	s_waitcnt lgkmcnt(0)
	v_mfma_f32_32x32x16_bf16 v[18:33], v[186:189], v[182:185], v[18:33]
	v_add_f32_e32 v110, v222, v110
	v_add_f32_e32 v97, v97, v110
	v_add_f32_e32 v96, v96, v97
	v_add_f32_e32 v96, v225, v96
	v_add_f32_e32 v96, v224, v96
	v_add_f32_e32 v96, v227, v96
	v_add_f32_e32 v96, v226, v96
	v_mfma_f32_32x32x16_bf16 v[66:81], v[214:217], v[134:137], v[66:81]
	v_add_f32_e32 v203, v180, v96
	v_cvt_pk_bf16_f32 v213, v91, v90
	v_cvt_pk_bf16_f32 v214, v93, v92
	v_cvt_pk_bf16_f32 v215, v95, v94
	ds_read2_b64 v[102:105], v209 offset0:76 offset1:78
	ds_read2_b64 v[106:109], v210 offset0:108 offset1:110
	s_waitcnt lgkmcnt(1)
	v_mfma_f32_32x32x16_bf16 v[2:17], v[102:105], v[212:215], v[2:17]
	s_waitcnt lgkmcnt(0)
	v_mfma_f32_32x32x16_bf16 v[18:33], v[106:109], v[212:215], v[18:33]
	s_cbranch_scc0 .LBB0_800
	v_add_u32_e32 v162, 0xffffff00, v160
	v_mov_b32_e32 v163, v161
	s_nop 0
	v_lshl_add_u64 v[162:163], s[94:95], 0, v[162:163]
	s_add_i32 s91, s29, 4
	s_mov_b64 s[8:9], -1
	s_cmp_lt_u32 s12, s91
	v_lshlrev_b32_e32 v158, 2, v178
	s_cbranch_scc1 .LBB0_823
	v_lshlrev_b32_e32 v0, 2, v178
	s_mov_b64 s[8:9], 0
